# attention work queue reordered: full units first (2 + 4 per workgroup), the 48 tiny context-query units last
# speedup vs baseline: 1.0404x; 1.0046x over previous
; DI void even_attention_phase(const Params& P, char* smem) {
;     ...
;     for (;;) {
;         __syncthreads();
;         if (ltid() == 0) *slot = (int)atomicAdd(wq, 1u);
;         __syncthreads();
;         const int u = *slot;
;         if (u >= NDIFF + NMLA) break;
;         if (u < NDIFF) {
;             const int qt = u % NQT, bh = u / NQT, h = bh & 3, b = bh >> 2;
;             const int q0 = qt < 32 ? qt * 256 : SEQ;
;             const int s0 = qt < 32 ? 0 : SEQ, n0 = qt < 32 ? NK / 64 : CTX / 64;
;             const bf16_t* V = VB + (size_t)(b * 4 + h) * NK * 128;
;             f32x16 o[4];
;             attend<64, 128, false>(QB + (size_t)(b * 8 + 2 * h) * NK * 64, q0, KB + (size_t)(b * 8 + 2 * h) * NK * 64, V, s0, n0, 0, 0, o, smem, na);
;             const int row = qrow_of(b, q0 + wave * 32 + l31);
;             bf16_t* dst = CC + (size_t)row * 1024 + 512 + h * 128;
; #pragma unroll
;             for (int d = 0; d < 4; ++d) store16(dst + d * 32, o[d], 1.f, hh);
;             f32x16 o2[4];
;             attend<64, 128, false>(QB + (size_t)(b * 8 + 2 * h + 1) * NK * 64, q0, KB + (size_t)(b * 8 + 2 * h + 1) * NK * 64, V, s0, n0, 0, 0, o2, smem, na);
;             float ss = 0.f;
; #pragma unroll
;             for (int d = 0; d < 4; ++d)
; #pragma unroll
;                 for (int q4 = 0; q4 < 4; ++q4) {
;                     const u32x2 w = *(const volatile u32x2*)(dst + d * 32 + 8 * q4 + 4 * hh);
;                     const float a0 = bflo(w.x) - lam * o2[d][4 * q4], a1 = bfhi(w.x) - lam * o2[d][4 * q4 + 1], a2 = bflo(w.y) - lam * o2[d][4 * q4 + 2], a3 = bfhi(w.y) - lam * o2[d][4 * q4 + 3];
;                     o[d][4 * q4] = a0; o[d][4 * q4 + 1] = a1; o[d][4 * q4 + 2] = a2; o[d][4 * q4 + 3] = a3;
;                     ss += (a0 * a0 + a1 * a1) + (a2 * a2 + a3 * a3);
;                 }
;             ss = xor32_sum(ss);
;             const float rn = rsqrtf(ss * (1.f / 128.f) + 1e-5f) * 0.8f;
; #pragma unroll
;             for (int d = 0; d < 4; ++d)
; #pragma unroll
;                 for (int q4 = 0; q4 < 4; ++q4) {
;                     const int c = d * 32 + 8 * q4 + 4 * hh;
;                     const f32x4 g = *(const f32x4*)(gsub + c);
;                     u32x2 w; w.x = pk2(o[d][4 * q4] * rn * g[0], o[d][4 * q4 + 1] * rn * g[1]); w.y = pk2(o[d][4 * q4 + 2] * rn * g[2], o[d][4 * q4 + 3] * rn * g[3]);
.LBB0_103:
	s_or_b64 exec, exec, s[0:1]
	s_mov_b64 s[0:1], src_shared_base
	s_add_i32 s0, 0, 0x11000
	s_cmp_lg_u32 s0, -1
	s_cselect_b32 s0, s0, 0
	s_cselect_b32 s1, s1, 0
	v_mov_b32_e32 v0, s0
	v_mov_b32_e32 v1, s1
	s_waitcnt lgkmcnt(0)
	s_barrier
	flat_load_dword v0, v[0:1] sc0 sc1
	s_waitcnt vmcnt(0)
	s_movk_i32 s0, 0x630
	s_waitcnt lgkmcnt(0)
	v_readfirstlane_b32 s2, v0
	s_nop 3
	s_lshr_b32 s3, s2, 5
	s_add_u32 s3, s3, s2
	s_sub_u32 s4, s2, 0x200
	s_lshr_b32 s4, s4, 5
	s_add_u32 s4, s4, s2
	s_add_u32 s4, s4, 16
	s_sub_u32 s5, s2, 0x600
	s_mul_i32 s5, s5, 33
	s_add_u32 s5, s5, 32
	s_sub_u32 s98, s2, 0x610
	s_mul_i32 s98, s98, 33
	s_add_u32 s98, s98, 0x230
	s_cmp_lt_u32 s2, 0x630
	s_cselect_b32 s99, s98, s2
	s_cmp_lt_u32 s2, 0x610
	s_cselect_b32 s99, s5, s99
	s_cmp_lt_u32 s2, 0x600
	s_cselect_b32 s99, s4, s99
	s_cmp_lt_u32 s2, 0x200
	s_cselect_b32 s99, s3, s99
	v_mov_b32_e32 v0, s99
	v_cmp_gt_i32_e32 vcc, s0, v0
	s_mov_b64 s[0:1], -1
	s_and_saveexec_b64 s[10:11], vcc
	s_cbranch_execz .LBB0_98
	s_movk_i32 s0, 0x20f
	v_cmp_lt_i32_e32 vcc, s0, v0
	s_and_saveexec_b64 s[0:1], vcc
	s_xor_b64 s[12:13], exec, s[0:1]
	s_cbranch_execz .LBB0_127
	v_add_u16_e32 v0, 0xfdf0, v0
	v_mul_u32_u24_e32 v1, 0xf83f, v0
	v_lshrrev_b32_e32 v140, 21, v1
	v_mul_lo_u16_e32 v1, 33, v140
	v_mul_u32_u24_e32 v116, 0xc6000, v140
	v_readlane_b32 s0, v253, 3
	v_sub_u16_e32 v0, v0, v1
	v_lshlrev_b32_e32 v172, 1, v116
	v_readlane_b32 s1, v253, 4
	v_cmp_gt_u16_e64 s[4:5], 32, v0
	v_lshlrev_b16_e32 v141, 8, v0
	v_lshl_add_u64 v[0:1], s[0:1], 0, v[172:173]
	v_readlane_b32 s0, v254, 29
	v_readlane_b32 s1, v254, 30
	v_mov_b32_e32 v16, v194
	s_movk_i32 s3, 0xc0
	v_lshl_add_u64 v[104:105], s[0:1], 0, v[172:173]
	v_readlane_b32 s0, v254, 31
	v_readlane_b32 s1, v254, 32
	v_and_b32_e32 v108, 31, v16
	v_bfe_u32 v17, v16, 5, 1
	v_mov_b64_e32 v[2:3], s[0:1]
	s_mov_b32 s0, 0x108000
	v_mad_u64_u32 v[106:107], s[0:1], v140, s0, v[2:3]
	v_ashrrev_i32_e32 v2, 1, v16
	v_and_b32_e32 v2, 0xffffffe0, v2
	v_or_b32_e32 v3, v108, v141
	v_add_u32_e32 v2, v3, v2
	v_mad_i64_i32 v[0:1], s[0:1], v2, s3, v[0:1]
	v_lshlrev_b32_e32 v172, 4, v17
	v_lshl_add_u64 v[0:1], v[0:1], 0, v[172:173]
	s_movk_i32 s0, 0x2ff
	global_load_dwordx4 v[100:103], v[0:1], off
	global_load_dwordx4 v[96:99], v[0:1], off offset:32
	global_load_dwordx4 v[92:95], v[0:1], off offset:64
	global_load_dwordx4 v[88:91], v[0:1], off offset:96
	global_load_dwordx4 v[84:87], v[0:1], off offset:128
	global_load_dwordx4 v[80:83], v[0:1], off offset:160
	v_cmp_lt_i32_e32 vcc, s0, v16
	v_add_u32_e32 v0, 0xfffffd00, v16
	s_mov_b32 s2, 0x2aaaaaab
	v_cndmask_b32_e32 v0, v16, v0, vcc
	v_mul_hi_i32 v1, v0, s2
	v_lshrrev_b32_e32 v2, 31, v1
	v_ashrrev_i32_e32 v1, 1, v1
	v_add_u32_e32 v124, v1, v2
	v_mad_u64_u32 v[12:13], s[0:1], v124, -12, v[0:1]
	v_cndmask_b32_e64 v117, v198, 0, s[4:5]
	v_lshlrev_b32_e32 v2, 3, v12
	v_add_u32_e32 v0, v124, v117
	v_ashrrev_i32_e32 v3, 31, v2
	v_mad_i64_i32 v[0:1], s[0:1], v0, s3, v[104:105]
	v_lshlrev_b64 v[118:119], 1, v[2:3]
	v_lshl_add_u64 v[0:1], v[0:1], 0, v[118:119]
	global_load_dwordx4 v[0:3], v[0:1], off
	s_movk_i32 s0, 0xff
	v_cmp_lt_i32_e32 vcc, s0, v16
	v_add_u32_e32 v8, 0xfffffe00, v16
	v_lshlrev_b32_e32 v143, 4, v12
	v_cndmask_b32_e32 v4, v199, v200, vcc
	v_add_u32_e32 v4, v4, v16
	v_mul_hi_i32 v5, v4, s2
	v_lshrrev_b32_e32 v6, 31, v5
	v_ashrrev_i32_e32 v5, 1, v5
	v_add_u32_e32 v125, v5, v6
	v_mad_u64_u32 v[14:15], s[0:1], v125, -12, v[4:5]
	v_add_u32_e32 v4, v125, v117
	v_mad_i64_i32 v[4:5], s[0:1], v4, s3, v[104:105]
	s_movk_i32 s0, 0x1ff
	s_nop 0
	v_cmp_lt_i32_e32 vcc, s0, v16
	v_lshlrev_b32_e32 v6, 3, v14
	s_movk_i32 s2, 0xd0
	v_cndmask_b32_e32 v13, v16, v8, vcc
	v_ashrrev_i32_e32 v8, 31, v13
	v_lshrrev_b32_e32 v8, 29, v8
	v_add_u32_e32 v8, v13, v8
	v_ashrrev_i32_e32 v126, 3, v8
	v_add_u32_e32 v8, v126, v117
	v_lshlrev_b32_e32 v10, 6, v126
	v_lshlrev_b32_e32 v11, 3, v13
	v_ashrrev_i32_e32 v9, 31, v8
	v_sub_u32_e32 v10, v11, v10
	v_ashrrev_i32_e32 v7, 31, v6
	v_lshlrev_b64 v[8:9], 7, v[8:9]
	v_ashrrev_i32_e32 v11, 31, v10
	v_mul_lo_u32 v142, v124, s2
	v_lshlrev_b64 v[120:121], 1, v[6:7]
	v_lshl_add_u64 v[8:9], v[106:107], 0, v[8:9]
	v_lshlrev_b64 v[122:123], 1, v[10:11]
	v_add_u32_e32 v15, 0, v142
	v_lshl_add_u64 v[4:5], v[4:5], 0, v[120:121]
	v_lshl_add_u64 v[8:9], v[8:9], 0, v[122:123]
	v_add_u32_e32 v114, v15, v143
	v_mul_lo_u32 v144, v125, s2
	global_load_dwordx4 v[4:7], v[4:5], off
	v_lshlrev_b32_e32 v145, 4, v14
	global_load_dwordx4 v[8:11], v[8:9], off
	s_barrier
	v_mul_lo_u32 v146, v126, s3
	v_add_u32_e32 v148, 0, v172
	v_bfe_u32 v18, v16, 2, 2
	v_and_b32_e32 v19, 16, v16
	v_mad_u32_u24 v60, v108, s2, v148
	v_lshl_or_b32 v109, v17, 2, v18
	s_waitcnt vmcnt(2)
	ds_write_b128 v114, v[0:3]
	v_add_u32_e32 v0, 0, v144
	v_lshlrev_b32_e32 v1, 7, v126
	v_lshlrev_b32_e32 v2, 4, v13
	v_add_u32_e32 v115, v0, v145
	v_add_u32_e32 v0, 0, v146
	v_sub_u32_e32 v147, v2, v1
	v_or_b32_e32 v2, 64, v117
	v_add_u32_e32 v127, v0, v147
	v_add_u32_e32 v0, v124, v2
	v_mad_i64_i32 v[0:1], s[0:1], v0, s3, v[104:105]
	v_lshl_add_u64 v[0:1], v[0:1], 0, v[118:119]
	global_load_dwordx4 v[64:67], v[0:1], off
	v_add_u32_e32 v0, v125, v2
	v_mad_i64_i32 v[0:1], s[0:1], v0, s3, v[104:105]
	v_lshl_add_u64 v[0:1], v[0:1], 0, v[120:121]
	global_load_dwordx4 v[68:71], v[0:1], off
	v_add_u32_e32 v0, v126, v2
	v_ashrrev_i32_e32 v1, 31, v0
	v_lshlrev_b64 v[0:1], 7, v[0:1]
	v_lshl_add_u64 v[0:1], v[106:107], 0, v[0:1]
	v_lshl_add_u64 v[0:1], v[0:1], 0, v[122:123]
	global_load_dwordx4 v[72:75], v[0:1], off
	v_lshlrev_b32_e32 v0, 2, v16
	v_and_or_b32 v36, v0, 12, v19
	s_waitcnt vmcnt(4)
	ds_write_b128 v115, v[4:7]
	s_waitcnt vmcnt(3)
	ds_write_b128 v127, v[8:11] offset:13312
	s_waitcnt lgkmcnt(0)
	s_barrier
; template <int DQK, int DV, bool NA>
; DI void attend(const bf16_t* __restrict__ Q, int q0, const bf16_t* __restrict__ Kb, const bf16_t* __restrict__ Vb,
;                int s0, int n0, int s1, int n1, f32x16 (&o)[DV / 32], char* smem, NAInfo na) {
;     ...
;                     for (int s = 0; s < NS; ++s) kf[s] = *(const bf16x8*)(sK + (sub * 32 + l31) * KS + (s * 16 + hh * 8) * 2);
;                     __builtin_amdgcn_sched_barrier(0);
; #pragma unroll
;                     for (int s = 0; s < NS; ++s) st = mfma32(kf[s], qf[s], st);
;                 }
;                 bf16x8 vf[NDT][2];
; #pragma unroll
;                 for (int d = 0; d < NDT; ++d)
; #pragma unroll
;                     for (int s2 = 0; s2 < 2; ++s2) {
;                         const char* vp = sV + (sub * 32 + 16 * s2 + 4 * hh + q) * VS + (d * 32 + dblk * 16 + 4 * p) * 2;
;                         vf[d][s2] = cat8(tr_read(vp), tr_read(vp + 8 * VS));
;                     }
;                 if (NA && t < n0) {
;                     const float* brow = rpb + (kr - na.qr + 7) * 31 + 15 - qc;
; #pragma unroll
;                     for (int r = 0; r < 16; ++r) {
;                         const int kc = sub * 32 + (r & 3) + 8 * (r >> 2) + 4 * hh;
;                         const bool valid = (kc >= cs) && (kc < cs + 16);
;                         const int bi = valid ? kc : cs;
;                         const float bias = brow[bi];
;                         st[r] = valid ? st[r] + bias : -INFINITY;
;                     }
;                 }
;                 float mx = st[0];
; #pragma unroll
;                 for (int r = 1; r < 16; ++r) mx = fmaxf(mx, st[r]);
;                 mx = xor32_max(mx);
;                 float rsum = 0.f;
;                 if (NA) {
;                     const float mnew = fmaxf(m, mx);
;                     const float muse = (mnew == -INFINITY) ? 0.f : mnew;
;                     const float alpha = __builtin_amdgcn_exp2f(m - muse);
;                     m = mnew;
;                     l *= alpha;
; #pragma unroll
;                     for (int d = 0; d < NDT; ++d)
; #pragma unroll
;                         for (int r = 0; r < 16; ++r) o[d][r] *= alpha;
; #pragma unroll
;                     for (int r = 0; r < 16; ++r) { st[r] = __builtin_amdgcn_exp2f(st[r] - muse); rsum += st[r]; }
;                 } else {
	ds_read_b128 v[0:3], v60
	ds_read_b128 v[16:19], v60 offset:32
	ds_read_b128 v[20:23], v60 offset:64
	ds_read_b128 v[24:27], v60 offset:96
	ds_read_b128 v[28:31], v60 offset:128
	ds_read_b128 v[32:35], v60 offset:160
	s_waitcnt lgkmcnt(5)
	v_mfma_f32_32x32x16_bf16 v[0:15], v[0:3], v[100:103], 0
	v_lshlrev_b32_e32 v152, 1, v36
	v_add_u32_e32 v149, 0, v152
	v_mad_u32_u24 v138, v109, s3, v149
	s_waitcnt lgkmcnt(4)
	v_mfma_f32_32x32x16_bf16 v[0:15], v[16:19], v[96:99], v[0:15]
	ds_read_b64_tr_b16 v[16:17], v138 offset:13312
	ds_read_b64_tr_b16 v[18:19], v138 offset:14848
	ds_read_b64_tr_b16 v[38:39], v138 offset:14912
	ds_read_b64_tr_b16 v[36:37], v138 offset:13376
	ds_read_b64_tr_b16 v[40:41], v138 offset:16384
	ds_read_b64_tr_b16 v[42:43], v138 offset:17920
	ds_read_b64_tr_b16 v[46:47], v138 offset:17984
	ds_read_b64_tr_b16 v[44:45], v138 offset:16448
	ds_read_b128 v[76:79], v60 offset:6656
	ds_read_b128 v[110:113], v60 offset:6688
	ds_read_b128 v[128:131], v60 offset:6720
	ds_read_b128 v[134:137], v60 offset:6752
	ds_read_b128 v[154:157], v60 offset:6784
	ds_read_b128 v[158:161], v60 offset:6816
	s_waitcnt lgkmcnt(14)
	v_mfma_f32_32x32x16_bf16 v[0:15], v[20:23], v[92:95], v[0:15]
	v_mfma_f32_32x32x16_bf16 v[0:15], v[24:27], v[88:91], v[0:15]
	v_mfma_f32_32x32x16_bf16 v[0:15], v[28:31], v[84:87], v[0:15]
	v_mfma_f32_32x32x16_bf16 v[0:15], v[32:35], v[80:83], v[0:15]
	s_nop 11
	v_max_f32_e32 v20, v1, v1
	v_max_f32_e32 v21, v0, v0
	v_max_f32_e32 v20, v21, v20
	v_max3_f32 v20, v20, v2, v3
	v_max3_f32 v20, v20, v4, v5
	v_max3_f32 v20, v20, v6, v7
	v_max3_f32 v20, v20, v8, v9
	v_max3_f32 v20, v20, v10, v11
	v_max3_f32 v20, v20, v12, v13
	v_max3_f32 v20, v20, v14, v15
	v_mov_b32_e32 v21, v20
	s_nop 1
	v_permlane32_swap_b32_e32 v20, v21
	v_max_f32_e32 v21, v21, v21
	v_max_f32_e32 v20, v20, v20
	v_max_f32_e32 v49, v20, v21
	v_sub_f32_e32 v0, v0, v49
	v_sub_f32_e32 v1, v1, v49
	v_sub_f32_e32 v2, v2, v49
	v_sub_f32_e32 v3, v3, v49
	v_sub_f32_e32 v4, v4, v49
	v_sub_f32_e32 v5, v5, v49
	v_sub_f32_e32 v6, v6, v49
	v_sub_f32_e32 v7, v7, v49
	v_exp_f32_e32 v0, v0
	v_exp_f32_e32 v20, v1
	v_exp_f32_e32 v48, v2
	v_exp_f32_e32 v50, v3
	v_exp_f32_e32 v4, v4
	v_exp_f32_e32 v5, v5
	v_exp_f32_e32 v6, v6
	v_exp_f32_e32 v7, v7
	v_sub_f32_e32 v9, v9, v49
	v_exp_f32_e32 v51, v9
	v_add_f32_e32 v9, 0, v0
	v_cvt_pk_bf16_f32 v0, v0, v20
	v_cvt_pk_bf16_f32 v1, v48, v50
	v_cvt_pk_bf16_f32 v2, v4, v5
	v_cvt_pk_bf16_f32 v3, v6, v7
	v_add_f32_e32 v9, v20, v9
	v_sub_f32_e32 v8, v8, v49
	s_waitcnt lgkmcnt(12)
	v_mfma_f32_32x32x16_bf16 v[16:31], v[16:19], v[0:3], 0
	v_sub_f32_e32 v10, v10, v49
	v_sub_f32_e32 v11, v11, v49
	v_sub_f32_e32 v12, v12, v49
	v_sub_f32_e32 v13, v13, v49
	v_sub_f32_e32 v14, v14, v49
	v_sub_f32_e32 v15, v15, v49
	v_add_f32_e32 v9, v48, v9
	v_exp_f32_e32 v8, v8
	v_exp_f32_e32 v52, v10
	v_exp_f32_e32 v53, v11
	v_exp_f32_e32 v54, v12
	v_exp_f32_e32 v55, v13
	v_exp_f32_e32 v56, v14
	v_exp_f32_e32 v57, v15
	v_add_f32_e32 v9, v50, v9
	v_add_f32_e32 v4, v4, v9
	v_add_f32_e32 v4, v5, v4
	v_add_f32_e32 v4, v6, v4
	v_cvt_pk_bf16_f32 v32, v8, v51
	v_cvt_pk_bf16_f32 v33, v52, v53
	v_cvt_pk_bf16_f32 v34, v54, v55
	v_cvt_pk_bf16_f32 v35, v56, v57
	v_add_f32_e32 v4, v7, v4
	s_waitcnt lgkmcnt(8)
	v_mfma_f32_32x32x16_bf16 v[16:31], v[40:43], v[32:35], v[16:31]
	v_add_f32_e32 v40, v8, v4
	v_mfma_f32_32x32x16_bf16 v[0:15], v[36:39], v[0:3], 0
	v_add_f32_e32 v36, v51, v40
	v_add_f32_e32 v36, v52, v36
	v_add_f32_e32 v36, v53, v36
	v_add_f32_e32 v36, v54, v36
	v_add_f32_e32 v36, v55, v36
	v_add_f32_e32 v36, v56, v36
	v_add_f32_e32 v48, v57, v36
	s_waitcnt lgkmcnt(6)
	v_mfma_f32_32x32x16_bf16 v[0:15], v[44:47], v[32:35], v[0:15]
	v_add_f32_e64 v132, v48, 0
	v_add_f32_e64 v133, v49, 0
	v_xor_b32_e32 v48, 0x80000000, v133
	v_mov_b32_e32 v49, v48
	v_mov_b32_e32 v50, v48
	v_mov_b32_e32 v51, v48
	v_mov_b32_e32 v52, v48
	v_mov_b32_e32 v53, v48
	v_mov_b32_e32 v54, v48
	v_mov_b32_e32 v55, v48
	v_mov_b32_e32 v56, v48
	v_mov_b32_e32 v57, v48
	v_mov_b32_e32 v58, v48
	v_mov_b32_e32 v59, v48
	v_mov_b32_e32 v60, v48
	v_mov_b32_e32 v61, v48
	v_mov_b32_e32 v62, v48
	v_mov_b32_e32 v63, v48
	v_mov_b64_e32 v[32:33], v[48:49]
	v_mov_b64_e32 v[34:35], v[50:51]
	v_mov_b64_e32 v[36:37], v[52:53]
	v_mov_b64_e32 v[38:39], v[54:55]
	v_mov_b64_e32 v[40:41], v[56:57]
	v_mov_b64_e32 v[42:43], v[58:59]
	v_mov_b64_e32 v[44:45], v[60:61]
	v_mov_b64_e32 v[46:47], v[62:63]
	ds_read_b64_tr_b16 v[54:55], v138 offset:19456
	ds_read_b64_tr_b16 v[56:57], v138 offset:20992
	ds_read_b64_tr_b16 v[52:53], v138 offset:21056
	ds_read_b64_tr_b16 v[50:51], v138 offset:19520
	s_waitcnt lgkmcnt(9)
	v_mfma_f32_32x32x16_bf16 v[32:47], v[76:79], v[100:103], v[32:47]
	ds_read_b64_tr_b16 v[58:59], v138 offset:22528
	ds_read_b64_tr_b16 v[60:61], v138 offset:24064
	ds_read_b64_tr_b16 v[78:79], v138 offset:24128
	ds_read_b64_tr_b16 v[76:77], v138 offset:22592
	s_mov_b32 s0, 0x41000000
	s_waitcnt lgkmcnt(12)
	v_mfma_f32_32x32x16_bf16 v[32:47], v[110:113], v[96:99], v[32:47]
	s_waitcnt lgkmcnt(11)
	v_mfma_f32_32x32x16_bf16 v[32:47], v[128:131], v[92:95], v[32:47]
	s_waitcnt lgkmcnt(10)
	v_mfma_f32_32x32x16_bf16 v[32:47], v[134:137], v[88:91], v[32:47]
	s_waitcnt lgkmcnt(9)
	v_mfma_f32_32x32x16_bf16 v[32:47], v[154:157], v[84:87], v[32:47]
	s_waitcnt lgkmcnt(8)
	v_mfma_f32_32x32x16_bf16 v[32:47], v[158:161], v[80:83], v[32:47]
	s_nop 11
	v_max_f32_e32 v49, v33, v33
	v_max_f32_e32 v62, v32, v32
	v_max_f32_e32 v49, v62, v49
	v_max3_f32 v49, v49, v34, v35
	v_max3_f32 v49, v49, v36, v37
	v_max3_f32 v49, v49, v38, v39
	v_max3_f32 v49, v49, v40, v41
	v_max3_f32 v49, v49, v42, v43
	v_max3_f32 v49, v49, v44, v45
	v_max3_f32 v49, v49, v46, v47
	v_mov_b32_e32 v62, v49
	s_nop 1
	v_permlane32_swap_b32_e32 v49, v62
	v_max_f32_e32 v62, v62, v62
	v_max_f32_e32 v49, v49, v49
	v_max_f32_e32 v49, v49, v62
	v_cmp_lt_f32_e32 vcc, s0, v49
	s_cbranch_vccz .LBB0_107
; template <int DQK, int DV, bool NA>
; DI void attend(const bf16_t* __restrict__ Q, int q0, const bf16_t* __restrict__ Kb, const bf16_t* __restrict__ Vb,
;                int s0, int n0, int s1, int n1, f32x16 (&o)[DV / 32], char* smem, NAInfo na) {
;     ...
;                     const bool first = (t == 0) && (sub == 0);
;                     if (first || __builtin_amdgcn_ballot_w64(mx > 8.f) != 0) {
;                         const float delta = first ? mx : fmaxf(mx, 0.f);
;                         const float alpha = first ? 1.f : __builtin_amdgcn_exp2f(-delta);
;                         m += delta;
;                         l *= alpha;
; #pragma unroll
;                         for (int d = 0; d < NDT; ++d)
; #pragma unroll
;                             for (int r = 0; r < 16; ++r) o[d][r] *= alpha;
; #pragma unroll
;                         for (int r = 0; r < 16; ++r) { st[r] -= delta; cinit[r] = -m; }
;                     }
	v_max_f32_e32 v48, v49, v49
	v_max_f32_e32 v48, 0, v48
	v_exp_f32_e64 v62, -v48
	v_pk_add_f32 v[32:33], v[32:33], v[48:49] op_sel_hi:[1,0] neg_lo:[0,1] neg_hi:[0,1]
	v_pk_add_f32 v[34:35], v[34:35], v[48:49] op_sel_hi:[1,0] neg_lo:[0,1] neg_hi:[0,1]
	v_pk_add_f32 v[36:37], v[36:37], v[48:49] op_sel_hi:[1,0] neg_lo:[0,1] neg_hi:[0,1]
	v_pk_mul_f32 v[30:31], v[30:31], v[62:63] op_sel_hi:[1,0]
	v_pk_mul_f32 v[28:29], v[28:29], v[62:63] op_sel_hi:[1,0]
	v_pk_mul_f32 v[26:27], v[26:27], v[62:63] op_sel_hi:[1,0]
	v_pk_mul_f32 v[24:25], v[24:25], v[62:63] op_sel_hi:[1,0]
	v_pk_mul_f32 v[22:23], v[22:23], v[62:63] op_sel_hi:[1,0]
	v_pk_mul_f32 v[20:21], v[20:21], v[62:63] op_sel_hi:[1,0]
	v_pk_mul_f32 v[18:19], v[18:19], v[62:63] op_sel_hi:[1,0]
	v_pk_mul_f32 v[16:17], v[16:17], v[62:63] op_sel_hi:[1,0]
	v_pk_mul_f32 v[14:15], v[14:15], v[62:63] op_sel_hi:[1,0]
	v_pk_mul_f32 v[12:13], v[12:13], v[62:63] op_sel_hi:[1,0]
	v_pk_mul_f32 v[10:11], v[10:11], v[62:63] op_sel_hi:[1,0]
	v_pk_mul_f32 v[8:9], v[8:9], v[62:63] op_sel_hi:[1,0]
	v_pk_mul_f32 v[6:7], v[6:7], v[62:63] op_sel_hi:[1,0]
	v_pk_mul_f32 v[4:5], v[4:5], v[62:63] op_sel_hi:[1,0]
	v_pk_mul_f32 v[2:3], v[2:3], v[62:63] op_sel_hi:[1,0]
	v_pk_mul_f32 v[0:1], v[0:1], v[62:63] op_sel_hi:[1,0]
	v_pk_mul_f32 v[62:63], v[132:133], v[62:63]
	v_add_f32_e32 v133, v133, v48
	v_pk_add_f32 v[38:39], v[38:39], v[48:49] op_sel_hi:[1,0] neg_lo:[0,1] neg_hi:[0,1]
	v_pk_add_f32 v[40:41], v[40:41], v[48:49] op_sel_hi:[1,0] neg_lo:[0,1] neg_hi:[0,1]
	v_pk_add_f32 v[42:43], v[42:43], v[48:49] op_sel_hi:[1,0] neg_lo:[0,1] neg_hi:[0,1]
	v_pk_add_f32 v[44:45], v[44:45], v[48:49] op_sel_hi:[1,0] neg_lo:[0,1] neg_hi:[0,1]
	v_pk_add_f32 v[46:47], v[46:47], v[48:49] op_sel_hi:[1,0] neg_lo:[0,1] neg_hi:[0,1]
	v_xor_b32_e32 v48, 0x80000000, v133
	v_mov_b32_e32 v132, v62
